# packed fp32 to scalar pairs (doc 7.5): the 8 v_pk_fma_f32 of the pipelined attention loop's score scaling become v_fma_f32 pairs
# baseline (speedup 1.0000x reference)
.LBB0_602:
	v_cndmask_b32_e64 v212, v216, v212, s[6:7]
	v_mul_f32_e32 v66, 0xbe0293ee, v212
	v_fmamk_f32 v67, v98, 0x3e0293ee, v66
	v_fmamk_f32 v68, v99, 0x3e0293ee, v66
	v_fmamk_f32 v69, v100, 0x3e0293ee, v66
	v_fmamk_f32 v70, v101, 0x3e0293ee, v66
	v_fmamk_f32 v71, v102, 0x3e0293ee, v66
	v_fmamk_f32 v72, v103, 0x3e0293ee, v66
	v_fmamk_f32 v73, v104, 0x3e0293ee, v66
	v_fmamk_f32 v74, v105, 0x3e0293ee, v66
	v_fmamk_f32 v75, v106, 0x3e0293ee, v66
	v_fmamk_f32 v76, v107, 0x3e0293ee, v66
	v_fmamk_f32 v77, v108, 0x3e0293ee, v66
	v_fmamk_f32 v78, v109, 0x3e0293ee, v66
	v_fmamk_f32 v79, v110, 0x3e0293ee, v66
	v_fmamk_f32 v80, v111, 0x3e0293ee, v66
	v_fmamk_f32 v81, v112, 0x3e0293ee, v66
	v_fmamk_f32 v98, v113, 0x3e0293ee, v66
	v_exp_f32_e32 v223, v67
	v_exp_f32_e32 v225, v68
	v_exp_f32_e32 v226, v69
	v_exp_f32_e32 v227, v70
	v_exp_f32_e32 v228, v71
	v_exp_f32_e32 v229, v72
	v_exp_f32_e32 v230, v73
	v_exp_f32_e32 v231, v74
	v_exp_f32_e32 v216, v75
	v_exp_f32_e32 v217, v76
	v_exp_f32_e32 v218, v77
	v_exp_f32_e32 v219, v78
	v_exp_f32_e32 v220, v79
	v_exp_f32_e32 v221, v80
	v_exp_f32_e32 v222, v81
	v_exp_f32_e32 v224, v98
	s_add_i32 s86, s86, 2
	v_add_f32_e32 v67, v232, v233
	s_add_u32 s22, s22, s20
	v_fmac_f32_e32 v67, v213, v166
	v_add_f32_e32 v166, v236, v237
	s_addc_u32 s23, s23, s21
	v_fmac_f32_e32 v166, v67, v235
	v_fma_f32 v98, v96, s54, v66
	v_fma_f32 v99, v97, s54, v66
	v_fma_f32 v100, v94, s54, v66
	v_fma_f32 v101, v95, s54, v66
	v_fma_f32 v102, v92, s54, v66
	v_fma_f32 v103, v93, s54, v66
	v_fma_f32 v104, v90, s54, v66
	v_fma_f32 v105, v91, s54, v66
	v_fma_f32 v106, v88, s54, v66
	v_fma_f32 v107, v89, s54, v66
	v_fma_f32 v108, v86, s54, v66
	v_fma_f32 v109, v87, s54, v66
	v_fma_f32 v110, v84, s54, v66
	v_fma_f32 v111, v85, s54, v66
	v_fma_f32 v112, v82, s54, v66
	v_fma_f32 v113, v83, s54, v66
	s_cmp_ge_i32 s86, s87
	v_add_u32_e32 v215, 0xffffff80, v215
	s_waitcnt lgkmcnt(0)
	s_barrier
	s_cbranch_scc1 .LBB0_605
	v_mov_b32_e32 v213, v234
	s_branch .LBB0_590
